# E47: one static s_setprio 1 for waves 4-7 across the attention tile loop (strategy 4: priority raise for the second wave of each SIMD)
# baseline (speedup 1.0000x reference)
.LBB0_2190:
	s_add_u32 s8, s50, s6
	s_addc_u32 s13, s51, s7
	s_add_u32 s14, s50, s80
	s_addc_u32 s15, s51, s81
	s_lshl_b32 s5, s12, 2
	s_add_i32 s5, s5, s34
	s_mul_hi_i32 s12, s4, s5
	s_mul_i32 s4, s4, s5
	s_add_u32 s4, s4, s10
	s_addc_u32 s5, s12, s11
	s_mul_i32 s10, s5, 0x180
	s_mul_hi_u32 s86, s4, 0x180
	s_add_i32 s86, s86, s10
	s_mul_i32 s87, s4, 0x180
	s_add_u32 s10, s14, s87
	s_addc_u32 s11, s15, s86
	s_lshl_b64 s[82:83], s[4:5], 8
	v_ashrrev_i32_e32 v36, 4, v162
	s_add_u32 s4, s8, s82
	v_lshlrev_b32_e32 v40, 3, v199
	v_ashrrev_i32_e32 v41, 3, v162
	s_movk_i32 s8, 0xc0
	v_ashrrev_i32_e32 v37, 31, v36
	s_addc_u32 s5, s13, s83
	v_and_b32_e32 v18, 0x78, v40
	v_add_u32_e32 v38, 32, v36
	v_and_b32_e32 v42, 7, v199
	v_mul_lo_u32 v16, v41, s8
	v_lshlrev_b64 v[48:49], 8, v[36:37]
	v_lshl_or_b32 v24, v42, 3, v16
	v_lshl_add_u64 v[16:17], s[4:5], 0, v[48:49]
	v_lshlrev_b32_e32 v18, 1, v18
	v_mov_b32_e32 v19, v161
	v_ashrrev_i32_e32 v39, 31, v38
	v_lshl_add_u64 v[52:53], v[16:17], 0, v[18:19]
	v_lshlrev_b64 v[16:17], 8, v[38:39]
	v_ashrrev_i32_e32 v25, 31, v24
	v_lshl_add_u64 v[16:17], s[4:5], 0, v[16:17]
	v_lshlrev_b64 v[50:51], 1, v[24:25]
	v_lshl_add_u64 v[20:21], v[16:17], 0, v[18:19]
	v_lshl_add_u64 v[54:55], s[10:11], 0, v[50:51]
	global_load_dwordx4 v[16:19], v[52:53], off
	s_nop 0
	global_load_dwordx4 v[20:23], v[20:21], off
	s_nop 0
	global_load_dwordx4 v[24:27], v[54:55], off
	global_load_dwordx4 v[28:31], v[54:55], off offset:128
	global_load_dwordx4 v[32:35], v[54:55], off offset:256
	s_waitcnt vmcnt(8)
	ds_write_b128 v139, v[4:7] offset:4096
	s_waitcnt vmcnt(7)
	ds_write_b128 v139, v[12:15] offset:5120
	s_waitcnt vmcnt(6)
	ds_write_b128 v139, v[0:3] offset:6144
	s_waitcnt vmcnt(5)
	ds_write_b128 v139, v[8:11] offset:7168
	s_movk_i32 s4, 0x180
	v_and_b32_e32 v1, 0xfffff0, v36
	v_lshlrev_b32_e32 v2, 1, v36
	v_lshrrev_b32_e32 v3, 1, v36
	v_and_b32_e32 v5, 3, v36
	v_and_b32_e32 v0, 0x70, v162
	v_mul_lo_u32 v7, v41, s4
	v_lshlrev_b32_e32 v9, 4, v42
	v_and_or_b32 v1, v2, 8, v1
	v_and_or_b32 v2, v3, 4, v5
	v_and_b32_e32 v3, 0xfffff0, v38
	v_lshlrev_b32_e32 v5, 1, v38
	v_bfe_u32 v4, v40, 5, 2
	v_bitop3_b32 v0, v9, v7, v0 bitop3:0xde
	v_lshrrev_b32_e32 v1, 1, v1
	v_and_or_b32 v3, v5, 8, v3
	v_lshlrev_b32_e32 v173, 4, v199
	v_add_u32_e32 v159, 0, v0
	v_or_b32_e32 v0, v1, v4
	v_lshrrev_b32_e32 v1, 1, v3
	v_lshlrev_b32_e32 v8, 3, v170
	v_mad_u32_u24 v80, v170, s4, 0
	v_and_b32_e32 v6, 48, v173
	s_movk_i32 s4, 0x70
	v_lshlrev_b32_e32 v2, 6, v2
	v_lshlrev_b32_e32 v0, 9, v0
	v_or_b32_e32 v1, v1, v4
	v_bitop3_b32 v155, v160, v8, s4 bitop3:0x78
	v_or3_b32 v0, v0, v2, v6
	v_lshlrev_b32_e32 v1, 9, v1
	v_add_u32_e32 v156, v80, v155
	v_or3_b32 v1, v1, v2, v6
	v_add_u32_e32 v163, 0, v0
	v_add_u32_e32 v164, 0, v1
	s_waitcnt vmcnt(0)
	v_and_b32_e32 v76, 0x70, v8
	v_bitop3_b32 v175, v160, v76, 32 bitop3:0x36
	v_add_u32_e32 v169, v80, v175
	v_bitop3_b32 v176, v160, v76, 64 bitop3:0x36
	v_add_u32_e32 v168, v80, v176
	s_movk_i32 s4, 0x60
	v_bitop3_b32 v177, v160, v76, s4 bitop3:0x36
	v_add_u32_e32 v167, v80, v177
	s_movk_i32 s4, 0x80
	v_bitop3_b32 v178, v160, v76, s4 bitop3:0x36
	v_add_u32_e32 v165, v80, v178
	s_movk_i32 s4, 0xa0
	v_bitop3_b32 v181, v160, v76, s4 bitop3:0x36
	v_add_u32_e32 v166, v80, v181
	v_bitop3_b32 v182, v160, v76, s8 bitop3:0x36
	v_add_u32_e32 v158, v80, v182
	s_movk_i32 s4, 0xe0
	v_bitop3_b32 v183, v160, v76, s4 bitop3:0x36
	v_add_u32_e32 v157, v80, v183
	s_waitcnt vmcnt(4)
	ds_write_b128 v163, v[16:19]
	s_waitcnt vmcnt(3)
	ds_write_b128 v164, v[20:23]
	s_waitcnt vmcnt(2)
	ds_write_b128 v159, v[24:27] offset:32768
	s_waitcnt vmcnt(1)
	ds_write_b128 v159, v[28:31] offset:32896
	s_waitcnt vmcnt(0)
	ds_write_b128 v159, v[32:35] offset:33024
	s_waitcnt lgkmcnt(0)
	s_barrier
	ds_read_b128 v[0:3], v156 offset:32768
	ds_read_b128 v[4:7], v156 offset:45056
	s_waitcnt lgkmcnt(1)
	v_mfma_f32_32x32x16_bf16 v[16:31], v[0:3], v[108:111], 0
	v_bitop3_b32 v184, v160, v76, s44 bitop3:0x36
	v_add_u32_e32 v154, v80, v184
	s_movk_i32 s5, 0x6000
	s_movk_i32 s4, 0x120
	v_add_co_u32_e32 v68, vcc, s5, v54
	v_bitop3_b32 v185, v160, v76, s4 bitop3:0x36
	s_waitcnt lgkmcnt(0)
	v_mfma_f32_32x32x16_bf16 v[32:47], v[4:7], v[108:111], 0
	ds_read_b128 v[0:3], v169 offset:32768
	ds_read_b128 v[4:7], v169 offset:45056
	v_addc_co_u32_e32 v69, vcc, 0, v55, vcc
	s_movk_i32 s4, 0x4000
	v_add_co_u32_e32 v54, vcc, s4, v52
	v_add_u32_e32 v153, v80, v185
	s_waitcnt lgkmcnt(1)
	v_mfma_f32_32x32x16_bf16 v[16:31], v[0:3], v[104:107], v[16:31]
	v_addc_co_u32_e32 v55, vcc, 0, v53, vcc
	v_add_co_u32_e32 v56, vcc, s5, v52
	s_movk_i32 s4, 0x140
	s_nop 0
	v_addc_co_u32_e32 v57, vcc, 0, v53, vcc
	s_waitcnt lgkmcnt(0)
	v_mfma_f32_32x32x16_bf16 v[32:47], v[4:7], v[104:107], v[32:47]
	ds_read_b128 v[0:3], v168 offset:32768
	ds_read_b128 v[4:7], v168 offset:45056
	v_bitop3_b32 v186, v160, v76, s4 bitop3:0x36
	v_add_u32_e32 v180, v80, v186
	s_movk_i32 s4, 0x160
	v_bitop3_b32 v187, v160, v76, s4 bitop3:0x36
	v_add_u32_e32 v179, v80, v187
	s_mov_b32 s8, s9
	s_waitcnt lgkmcnt(1)
	v_mfma_f32_32x32x16_bf16 v[16:31], v[0:3], v[100:103], v[16:31]
	s_mov_b32 s10, s9
	s_mov_b32 s11, s9
	s_mov_b32 s12, s9
	s_mov_b32 s13, s9
	s_mov_b32 s14, s9
	s_mov_b32 s15, s9
	s_mov_b32 s16, s9
	s_waitcnt lgkmcnt(0)
	v_mfma_f32_32x32x16_bf16 v[32:47], v[4:7], v[100:103], v[32:47]
	ds_read_b128 v[0:3], v167 offset:32768
	ds_read_b128 v[4:7], v167 offset:45056
	s_mov_b32 s17, s9
	s_mov_b32 s18, s9
	s_mov_b32 s19, s9
	s_mov_b32 s20, s9
	s_mov_b32 s21, s9
	s_mov_b32 s22, s9
	s_waitcnt lgkmcnt(1)
	v_mfma_f32_32x32x16_bf16 v[16:31], v[0:3], v[96:99], v[16:31]
	s_mov_b32 s23, s9
	s_movk_i32 s68, 0xc0
	s_mov_b32 s85, 2
	v_add_u32_e32 v190, 0xe000, v80
	v_cmp_gt_u32_e64 s[4:5], 32, v141
	v_mov_b32_e32 v151, 0
	s_waitcnt lgkmcnt(0)
	v_mfma_f32_32x32x16_bf16 v[32:47], v[4:7], v[96:99], v[32:47]
	ds_read_b128 v[0:3], v165 offset:32768
	ds_read_b128 v[4:7], v139
	ds_read_b128 v[8:11], v165 offset:45056
	ds_read_b128 v[12:15], v139 offset:1024
	s_waitcnt lgkmcnt(2)
	v_mfma_f32_32x32x16_bf16 v[16:31], v[0:3], v[4:7], v[16:31]
	s_waitcnt lgkmcnt(1)
	v_mfma_f32_32x32x16_bf16 v[32:47], v[8:11], v[4:7], v[32:47]
	ds_read_b128 v[0:3], v166 offset:32768
	ds_read_b128 v[4:7], v166 offset:45056
	s_waitcnt lgkmcnt(1)
	v_mfma_f32_32x32x16_bf16 v[16:31], v[0:3], v[12:15], v[16:31]
	s_waitcnt lgkmcnt(0)
	v_mfma_f32_32x32x16_bf16 v[32:47], v[4:7], v[12:15], v[32:47]
	ds_read_b128 v[0:3], v158 offset:32768
	ds_read_b128 v[4:7], v139 offset:2048
	ds_read_b128 v[8:11], v158 offset:45056
	ds_read_b128 v[12:15], v139 offset:3072
	s_waitcnt lgkmcnt(2)
	v_mfma_f32_32x32x16_bf16 v[16:31], v[0:3], v[4:7], v[16:31]
	ds_read_b128 v[0:3], v157 offset:32768
	s_waitcnt lgkmcnt(2)
	v_mfma_f32_32x32x16_bf16 v[32:47], v[8:11], v[4:7], v[32:47]
	ds_read_b128 v[4:7], v157 offset:45056
	s_waitcnt lgkmcnt(1)
	v_mfma_f32_32x32x16_bf16 v[16:31], v[0:3], v[12:15], v[16:31]
	ds_read_b128 v[0:3], v154 offset:32768
	s_waitcnt lgkmcnt(1)
	v_mfma_f32_32x32x16_bf16 v[32:47], v[4:7], v[12:15], v[32:47]
	ds_read_b128 v[4:7], v139 offset:4096
	ds_read_b128 v[8:11], v154 offset:45056
	ds_read_b128 v[12:15], v139 offset:5120
	s_waitcnt lgkmcnt(2)
	v_mfma_f32_32x32x16_bf16 v[16:31], v[0:3], v[4:7], v[16:31]
	ds_read_b128 v[0:3], v153 offset:32768
	global_load_dwordx4 v[52:55], v[54:55], off
	s_nop 0
	global_load_dwordx4 v[56:59], v[56:57], off
	s_nop 0
	global_load_dwordx4 v[60:63], v[68:69], off
	global_load_dwordx4 v[64:67], v[68:69], off offset:128
	s_nop 0
	global_load_dwordx4 v[68:71], v[68:69], off offset:256
	s_waitcnt lgkmcnt(2)
	v_mfma_f32_32x32x16_bf16 v[32:47], v[8:11], v[4:7], v[32:47]
	ds_read_b128 v[4:7], v153 offset:45056
	v_and_b32_e32 v8, 0x3fffffc0, v162
	v_lshlrev_b32_e32 v9, 3, v141
	v_lshl_add_u32 v137, v8, 2, s0
	v_lshl_add_u32 v174, v170, 2, v137
	s_waitcnt lgkmcnt(1)
	v_mfma_f32_32x32x16_bf16 v[16:31], v[0:3], v[12:15], v[16:31]
	v_and_b32_e32 v0, 0xc0, v140
	v_and_or_b32 v8, v9, 24, v0
	ds_read_b128 v[0:3], v180 offset:32768
	v_and_b32_e32 v9, 0x100, v9
	s_waitcnt lgkmcnt(1)
	v_mfma_f32_32x32x16_bf16 v[32:47], v[4:7], v[12:15], v[32:47]
	v_lshlrev_b32_e32 v4, 1, v141
	v_and_b32_e32 v10, 32, v4
	ds_read_b128 v[4:7], v139 offset:6144
	v_or3_b32 v81, v8, v10, v9
	ds_read_b128 v[8:11], v180 offset:45056
	ds_read_b128 v[72:75], v139 offset:7168
	ds_read_b128 v[76:79], v179 offset:45056
	v_add_u32_e32 v152, 0, v81
	s_waitcnt lgkmcnt(3)
	v_mfma_f32_32x32x16_bf16 v[16:31], v[0:3], v[4:7], v[16:31]
	ds_read_b128 v[0:3], v179 offset:32768
	s_waitcnt vmcnt(0)
	s_waitcnt vmcnt(4)
	ds_write_b128 v163, v[52:55] offset:16384
	s_waitcnt vmcnt(3)
	ds_write_b128 v164, v[56:59] offset:16384
	s_waitcnt vmcnt(2)
	ds_write_b128 v159, v[60:63] offset:57344
	s_waitcnt vmcnt(1)
	ds_write_b128 v159, v[64:67] offset:57472
	s_waitcnt vmcnt(0)
	ds_write_b128 v159, v[68:71] offset:57600
	s_waitcnt lgkmcnt(8)
	v_mfma_f32_32x32x16_bf16 v[32:47], v[8:11], v[4:7], v[32:47]
	s_waitcnt lgkmcnt(0)
	s_barrier
	v_mfma_f32_32x32x16_bf16 v[16:31], v[0:3], v[72:75], v[16:31]
	v_mov_b64_e32 v[0:1], s[8:9]
	v_mov_b64_e32 v[2:3], s[10:11]
	v_mov_b64_e32 v[4:5], s[12:13]
	v_mov_b64_e32 v[6:7], s[14:15]
	v_mov_b64_e32 v[8:9], s[16:17]
	v_mov_b64_e32 v[10:11], s[18:19]
	v_mov_b64_e32 v[12:13], s[20:21]
	v_mfma_f32_32x32x16_bf16 v[32:47], v[76:79], v[72:75], v[32:47]
	s_nop 3
	v_max_f32_e32 v72, v17, v17
	v_max_f32_e32 v73, v16, v16
	v_max_f32_e32 v72, v73, v72
	v_max3_f32 v72, v72, v18, v19
	v_max3_f32 v72, v72, v20, v21
	v_max3_f32 v72, v72, v22, v23
	v_max3_f32 v72, v72, v24, v25
	v_max3_f32 v72, v72, v26, v27
	v_max3_f32 v72, v72, v28, v29
	v_max3_f32 v72, v72, v30, v31
	v_max3_f32 v72, v72, v32, v33
	v_max3_f32 v72, v72, v34, v35
	v_max3_f32 v72, v72, v36, v37
	v_max3_f32 v72, v72, v38, v39
	v_max3_f32 v72, v72, v40, v41
	v_max3_f32 v72, v72, v42, v43
	v_max3_f32 v72, v72, v44, v45
	v_max3_f32 v72, v72, v46, v47
	v_mov_b32_e32 v73, v72
	s_nop 1
	v_permlane32_swap_b32_e32 v72, v73
	v_max_f32_e32 v73, v73, v73
	v_max_f32_e32 v72, v72, v72
	v_max_f32_e32 v72, v72, v73
	v_add_f32_e32 v73, 0x7149f2ca, v72
	v_cmp_ge_f32_e32 vcc, s1, v73
	s_cmp_eq_u64 vcc, exec
	v_max_f32_e32 v52, 0xf149f2ca, v72
	s_cselect_b64 vcc, -1, 0
	v_cndmask_b32_e32 v188, v52, v198, vcc
	v_sub_f32_e32 v53, 0xf149f2ca, v52
	v_mul_f32_e32 v52, 0xbdd53b94, v188
	v_fmamk_f32 v16, v16, 0x3dd53b94, v52
	v_exp_f32_e32 v133, v16
	v_fmamk_f32 v16, v17, 0x3dd53b94, v52
	v_exp_f32_e32 v214, v16
	v_fmamk_f32 v16, v18, 0x3dd53b94, v52
	v_exp_f32_e32 v134, v16
	v_fmamk_f32 v16, v19, 0x3dd53b94, v52
	v_exp_f32_e32 v215, v16
	v_fmamk_f32 v16, v20, 0x3dd53b94, v52
	v_exp_f32_e32 v213, v16
	v_fmamk_f32 v16, v21, 0x3dd53b94, v52
	v_exp_f32_e32 v216, v16
	v_fmamk_f32 v16, v22, 0x3dd53b94, v52
	v_exp_f32_e32 v135, v16
	v_fmamk_f32 v16, v23, 0x3dd53b94, v52
	v_exp_f32_e32 v212, v16
	v_fmamk_f32 v16, v24, 0x3dd53b94, v52
	v_mul_f32_e32 v53, 0x3dd53b94, v53
	v_exp_f32_e32 v146, v16
	v_fmamk_f32 v16, v25, 0x3dd53b94, v52
	v_exp_f32_e32 v53, v53
	v_exp_f32_e32 v148, v16
	v_fmamk_f32 v16, v26, 0x3dd53b94, v52
	v_mov_b64_e32 v[14:15], s[22:23]
	v_exp_f32_e32 v147, v16
	v_fmamk_f32 v16, v27, 0x3dd53b94, v52
	s_add_i32 s8, 0, 0x4000
	v_exp_f32_e32 v149, v16
	v_fmamk_f32 v16, v28, 0x3dd53b94, v52
	s_add_u32 s10, s80, s87
	v_exp_f32_e32 v128, v16
	v_fmamk_f32 v16, v29, 0x3dd53b94, v52
	s_addc_u32 s11, s81, s86
	v_pk_fma_f32 v[112:113], v[46:47], s[72:73], v[52:53] op_sel_hi:[1,0,0]
	v_pk_fma_f32 v[118:119], v[44:45], s[72:73], v[52:53] op_sel_hi:[1,0,0]
	v_pk_fma_f32 v[122:123], v[42:43], s[72:73], v[52:53] op_sel_hi:[1,0,0]
	v_pk_fma_f32 v[114:115], v[40:41], s[72:73], v[52:53] op_sel_hi:[1,0,0]
	v_pk_fma_f32 v[116:117], v[38:39], s[72:73], v[52:53] op_sel_hi:[1,0,0]
	v_pk_fma_f32 v[120:121], v[36:37], s[72:73], v[52:53] op_sel_hi:[1,0,0]
	v_pk_fma_f32 v[124:125], v[34:35], s[72:73], v[52:53] op_sel_hi:[1,0,0]
	v_pk_fma_f32 v[126:127], v[32:33], s[72:73], v[52:53] op_sel_hi:[1,0,0]
	v_exp_f32_e32 v130, v16
	v_fmamk_f32 v16, v30, 0x3dd53b94, v52
	v_fmac_f32_e32 v52, 0x3dd53b94, v31
	s_add_u32 s6, s6, s82
	v_exp_f32_e32 v129, v16
	v_exp_f32_e32 v131, v52
	s_addc_u32 s7, s7, s83
	v_and_b32_e32 v18, 15, v199
	v_lshl_add_u64 v[16:17], s[6:7], 0, v[48:49]
	v_lshlrev_b32_e32 v18, 4, v18
	v_mov_b32_e32 v19, v161
	v_cndmask_b32_e64 v189, v53, 1.0, vcc
	v_lshl_add_u64 v[142:143], s[10:11], 0, v[50:51]
	v_lshl_add_u64 v[144:145], v[16:17], 0, v[18:19]
	v_mov_b64_e32 v[62:63], v[14:15]
	v_mov_b64_e32 v[46:47], v[14:15]
	v_mov_b64_e32 v[30:31], v[14:15]
	v_add_u32_e32 v150, s8, v81
	v_mov_b64_e32 v[60:61], v[12:13]
	v_mov_b64_e32 v[58:59], v[10:11]
	v_mov_b64_e32 v[56:57], v[8:9]
	v_mov_b64_e32 v[54:55], v[6:7]
	v_mov_b64_e32 v[52:53], v[4:5]
	v_mov_b64_e32 v[50:51], v[2:3]
	v_mov_b64_e32 v[48:49], v[0:1]
	v_mov_b64_e32 v[44:45], v[12:13]
	v_mov_b64_e32 v[42:43], v[10:11]
	v_mov_b64_e32 v[40:41], v[8:9]
	v_mov_b64_e32 v[38:39], v[6:7]
	v_mov_b64_e32 v[36:37], v[4:5]
	v_mov_b64_e32 v[34:35], v[2:3]
	v_mov_b64_e32 v[32:33], v[0:1]
	v_mov_b64_e32 v[28:29], v[12:13]
	v_mov_b64_e32 v[26:27], v[10:11]
	v_mov_b64_e32 v[24:25], v[8:9]
	v_mov_b64_e32 v[22:23], v[6:7]
	v_mov_b64_e32 v[20:21], v[4:5]
	v_mov_b64_e32 v[18:19], v[2:3]
	v_mov_b64_e32 v[16:17], v[0:1]
	v_readlane_b32 s86, v254, 19
	v_readlane_b32 s87, v254, 20
	s_cmp_lt_u32 s38, 0x100
	s_cbranch_scc1 .Lattn_prio_skip
	s_setprio 1
.Lattn_prio_skip:
.LBB0_2191:
	ds_read_b128 v[64:67], v156 offset:57344
	ds_read_b128 v[200:203], v169 offset:57344
	v_add_u32_e32 v191, v190, v155
	ds_read_b128 v[68:71], v191 offset:12288
	v_add_u32_e32 v193, v190, v175
	ds_read_b128 v[204:207], v193 offset:12288
	v_add_u32_e32 v192, v190, v176
	v_add_f32_e32 v132, 0, v133
	v_add_f32_e32 v132, v214, v132
	s_waitcnt lgkmcnt(3)
	v_mfma_f32_32x32x16_bf16 v[80:95], v[64:67], v[108:111], 0
	v_add_f32_e32 v132, v134, v132
	v_add_f32_e32 v132, v215, v132
	v_add_f32_e32 v132, v213, v132
	v_add_f32_e32 v132, v216, v132
	v_add_f32_e32 v132, v135, v132
	v_add_f32_e32 v132, v212, v132
	v_add_f32_e32 v132, v146, v132
	s_waitcnt lgkmcnt(2)
	v_mfma_f32_32x32x16_bf16 v[80:95], v[200:203], v[104:107], v[80:95]
	ds_read_b128 v[200:203], v168 offset:57344
	v_add_f32_e32 v132, v148, v132
	v_add_f32_e32 v132, v147, v132
	v_add_f32_e32 v132, v149, v132
	v_exp_f32_e32 v126, v126
	v_add_f32_e32 v132, v128, v132
	v_exp_f32_e32 v127, v127
	s_waitcnt lgkmcnt(2)
	v_mfma_f32_32x32x16_bf16 v[64:79], v[68:71], v[108:111], 0
	v_add_f32_e32 v132, v130, v132
	v_exp_f32_e32 v124, v124
	v_add_f32_e32 v132, v129, v132
	v_exp_f32_e32 v125, v125
	v_add_f32_e32 v132, v131, v132
	v_exp_f32_e32 v120, v120
	v_add_f32_e32 v132, v126, v132
	s_waitcnt lgkmcnt(1)
	v_mfma_f32_32x32x16_bf16 v[64:79], v[204:207], v[104:107], v[64:79]
	ds_read_b128 v[204:207], v192 offset:12288
	v_exp_f32_e32 v121, v121
	v_add_f32_e32 v132, v127, v132
	v_exp_f32_e32 v116, v116
	v_add_f32_e32 v132, v124, v132
	v_exp_f32_e32 v117, v117
	v_add_f32_e32 v132, v125, v132
	s_waitcnt lgkmcnt(1)
	v_mfma_f32_32x32x16_bf16 v[80:95], v[200:203], v[100:103], v[80:95]
	v_add_u32_e32 v200, v190, v177
	v_add_u32_e32 v201, v190, v178
	v_exp_f32_e32 v114, v114
	v_add_f32_e32 v132, v120, v132
	v_exp_f32_e32 v115, v115
	v_add_f32_e32 v132, v121, v132
	v_exp_f32_e32 v122, v122
	s_waitcnt lgkmcnt(0)
	v_mfma_f32_32x32x16_bf16 v[64:79], v[204:207], v[100:103], v[64:79]
	ds_read_b128 v[202:205], v167 offset:57344
	ds_read_b128 v[206:209], v200 offset:12288
	v_add_f32_e32 v132, v116, v132
	v_exp_f32_e32 v123, v123
	v_add_f32_e32 v132, v117, v132
	v_exp_f32_e32 v118, v118
	v_add_f32_e32 v132, v114, v132
	s_waitcnt lgkmcnt(1)
	v_mfma_f32_32x32x16_bf16 v[80:95], v[202:205], v[96:99], v[80:95]
	ds_read_b128 v[202:205], v165 offset:57344
	v_exp_f32_e32 v119, v119
	v_add_f32_e32 v132, v115, v132
	v_exp_f32_e32 v112, v112
	v_add_f32_e32 v132, v122, v132
	v_exp_f32_e32 v113, v113
	v_add_f32_e32 v132, v123, v132
	s_waitcnt lgkmcnt(1)
	v_mfma_f32_32x32x16_bf16 v[64:79], v[206:209], v[96:99], v[64:79]
	ds_read_b128 v[206:209], v201 offset:12288
	ds_read_b128 v[224:227], v139
	v_add_f32_e32 v132, v118, v132
	v_add_f32_e32 v132, v119, v132
	v_add_f32_e32 v132, v112, v132
	s_waitcnt lgkmcnt(0)
	v_mfma_f32_32x32x16_bf16 v[64:79], v[206:209], v[224:227], v[64:79]
	ds_read_b128 v[206:209], v166 offset:57344
	v_mfma_f32_32x32x16_bf16 v[80:95], v[202:205], v[224:227], v[80:95]
	v_add_u32_e32 v204, v190, v181
	ds_read_b128 v[224:227], v204 offset:12288
	ds_read_b128 v[228:231], v139 offset:1024
	v_add_u32_e32 v202, v190, v182
	v_add_u32_e32 v203, v190, v183
	v_add_u32_e32 v205, v190, v185
	s_waitcnt lgkmcnt(0)
	v_mfma_f32_32x32x16_bf16 v[80:95], v[206:209], v[228:231], v[80:95]
	ds_read_b128 v[206:209], v158 offset:57344
	v_mfma_f32_32x32x16_bf16 v[64:79], v[224:227], v[228:231], v[64:79]
	ds_read_b128 v[224:227], v202 offset:12288
	ds_read_b128 v[228:231], v139 offset:2048
	s_waitcnt lgkmcnt(0)
	v_mfma_f32_32x32x16_bf16 v[80:95], v[206:209], v[228:231], v[80:95]
	ds_read_b128 v[206:209], v157 offset:57344
	v_mfma_f32_32x32x16_bf16 v[64:79], v[224:227], v[228:231], v[64:79]
	ds_read_b128 v[224:227], v203 offset:12288
	ds_read_b128 v[228:231], v139 offset:3072
	s_waitcnt lgkmcnt(0)
	v_mfma_f32_32x32x16_bf16 v[80:95], v[206:209], v[228:231], v[80:95]
	ds_read_b128 v[208:211], v154 offset:57344
	v_add_u32_e32 v206, v190, v184
	v_add_u32_e32 v207, v190, v186
	v_mfma_f32_32x32x16_bf16 v[64:79], v[224:227], v[228:231], v[64:79]
	ds_read_b128 v[224:227], v206 offset:12288
	ds_read_b128 v[228:231], v139 offset:4096
	s_waitcnt lgkmcnt(0)
	v_mfma_f32_32x32x16_bf16 v[80:95], v[208:211], v[228:231], v[80:95]
	ds_read_b128 v[208:211], v153 offset:57344
	v_mfma_f32_32x32x16_bf16 v[64:79], v[224:227], v[228:231], v[64:79]
	ds_read_b128 v[224:227], v205 offset:12288
	ds_read_b128 v[228:231], v139 offset:5120
	s_waitcnt lgkmcnt(0)
	v_mfma_f32_32x32x16_bf16 v[80:95], v[208:211], v[228:231], v[80:95]
	ds_read_b128 v[208:211], v180 offset:57344
	v_mfma_f32_32x32x16_bf16 v[64:79], v[224:227], v[228:231], v[64:79]
	ds_read_b128 v[224:227], v207 offset:12288
	ds_read_b128 v[228:231], v139 offset:6144
	s_waitcnt lgkmcnt(0)
	v_mfma_f32_32x32x16_bf16 v[64:79], v[224:227], v[228:231], v[64:79]
	ds_read_b128 v[224:227], v179 offset:57344
	v_mfma_f32_32x32x16_bf16 v[80:95], v[208:211], v[228:231], v[80:95]
	v_add_u32_e32 v208, v190, v187
	ds_read_b128 v[228:231], v208 offset:12288
	ds_read_b128 v[232:235], v139 offset:7168
	v_add_f32_e32 v209, v113, v132
	v_mov_b32_e32 v210, v209
	v_cvt_pk_bf16_f32 v132, v133, v214
	v_cvt_pk_bf16_f32 v133, v134, v215
	v_cvt_pk_bf16_f32 v134, v213, v216
	s_waitcnt lgkmcnt(0)
	v_mfma_f32_32x32x16_bf16 v[80:95], v[224:227], v[232:235], v[80:95]
	v_permlane32_swap_b32_e32 v209, v210
	v_cvt_pk_bf16_f32 v135, v135, v212
	v_permlane32_swap_b32_e32 v132, v134
	v_cvt_pk_bf16_f32 v212, v146, v148
	v_cvt_pk_bf16_f32 v213, v147, v149
	v_mfma_f32_32x32x16_bf16 v[64:79], v[228:231], v[232:235], v[64:79]
	v_cvt_pk_bf16_f32 v214, v128, v130
	v_cvt_pk_bf16_f32 v215, v129, v131
	v_cvt_pk_bf16_f32 v216, v126, v127
	v_cvt_pk_bf16_f32 v217, v124, v125
	v_cvt_pk_bf16_f32 v218, v120, v121
	v_cvt_pk_bf16_f32 v219, v116, v117
	v_cvt_pk_bf16_f32 v224, v114, v115
	v_cvt_pk_bf16_f32 v225, v122, v123
	v_cvt_pk_bf16_f32 v226, v118, v119
	v_cvt_pk_bf16_f32 v227, v112, v113
	v_permlane32_swap_b32_e32 v133, v135
	v_permlane32_swap_b32_e32 v212, v214
	v_permlane32_swap_b32_e32 v213, v215
	v_permlane32_swap_b32_e32 v216, v218
	v_permlane32_swap_b32_e32 v217, v219
	v_permlane32_swap_b32_e32 v224, v226
	v_permlane32_swap_b32_e32 v225, v227
	v_lshl_add_u64 v[146:147], s[50:51], 0, v[144:145]
	s_mov_b32 s6, 0x8000
	v_add_co_u32_e32 v112, vcc, s6, v146
	s_mov_b32 s6, 0xa000
	s_nop 0
	v_addc_co_u32_e32 v113, vcc, 0, v147, vcc
	v_add_co_u32_e32 v116, vcc, s6, v146
	v_lshl_add_u64 v[148:149], s[50:51], 0, v[142:143]
	s_nop 0
	v_addc_co_u32_e32 v117, vcc, 0, v147, vcc
	v_add_co_u32_e32 v128, vcc, s64, v148
	global_load_dwordx4 v[112:115], v[112:113], off
	s_nop 0
	global_load_dwordx4 v[116:119], v[116:117], off
	v_addc_co_u32_e32 v129, vcc, 0, v149, vcc
	global_load_dwordx4 v[120:123], v[128:129], off
	global_load_dwordx4 v[124:127], v[128:129], off offset:128
	s_nop 0
	global_load_dwordx4 v[128:131], v[128:129], off offset:256
	ds_read_b64_tr_b16 v[228:229], v152 offset:0
	ds_read_b64_tr_b16 v[230:231], v152 offset:0x800
	ds_read_b64_tr_b16 v[232:233], v152 offset:0x1000
	ds_read_b64_tr_b16 v[234:235], v152 offset:0x1800
	ds_read_b64_tr_b16 v[236:237], v152 offset:0x2000
	ds_read_b64_tr_b16 v[238:239], v152 offset:0x2800
	ds_read_b64_tr_b16 v[240:241], v152 offset:0x3000
	ds_read_b64_tr_b16 v[242:243], v152 offset:0x3800
	s_waitcnt lgkmcnt(0)
	s_nop 0
	v_mfma_f32_32x32x16_bf16 v[0:15], v[132:135], v[228:231], v[0:15]
	ds_read_b64_tr_b16 v[228:229], v152 offset:0x200
	ds_read_b64_tr_b16 v[230:231], v152 offset:0xa00
	v_mfma_f32_32x32x16_bf16 v[0:15], v[212:215], v[232:235], v[0:15]
	ds_read_b64_tr_b16 v[232:233], v152 offset:0x1200
	ds_read_b64_tr_b16 v[234:235], v152 offset:0x1a00
	v_mfma_f32_32x32x16_bf16 v[0:15], v[216:219], v[236:239], v[0:15]
	ds_read_b64_tr_b16 v[236:237], v152 offset:0x2200
	ds_read_b64_tr_b16 v[238:239], v152 offset:0x2a00
	v_mfma_f32_32x32x16_bf16 v[0:15], v[224:227], v[240:243], v[0:15]
	ds_read_b64_tr_b16 v[240:241], v152 offset:0x3200
	ds_read_b64_tr_b16 v[242:243], v152 offset:0x3a00
	s_waitcnt lgkmcnt(0)
	v_mfma_f32_32x32x16_bf16 v[48:63], v[132:135], v[228:231], v[48:63]
	ds_read_b64_tr_b16 v[228:229], v152 offset:0x400
	ds_read_b64_tr_b16 v[230:231], v152 offset:0xc00
	v_mfma_f32_32x32x16_bf16 v[48:63], v[212:215], v[232:235], v[48:63]
	ds_read_b64_tr_b16 v[232:233], v152 offset:0x1400
	ds_read_b64_tr_b16 v[234:235], v152 offset:0x1c00
	v_mfma_f32_32x32x16_bf16 v[48:63], v[216:219], v[236:239], v[48:63]
	ds_read_b64_tr_b16 v[236:237], v152 offset:0x2400
	ds_read_b64_tr_b16 v[238:239], v152 offset:0x2c00
	v_mfma_f32_32x32x16_bf16 v[48:63], v[224:227], v[240:243], v[48:63]
	ds_read_b64_tr_b16 v[240:241], v152 offset:0x3400
	ds_read_b64_tr_b16 v[242:243], v152 offset:0x3c00
	s_waitcnt lgkmcnt(0)
	v_mfma_f32_32x32x16_bf16 v[32:47], v[132:135], v[228:231], v[32:47]
	ds_read_b64_tr_b16 v[228:229], v152 offset:0x600
	ds_read_b64_tr_b16 v[230:231], v152 offset:0xe00
	v_mfma_f32_32x32x16_bf16 v[32:47], v[212:215], v[232:235], v[32:47]
	ds_read_b64_tr_b16 v[232:233], v152 offset:0x1600
	ds_read_b64_tr_b16 v[234:235], v152 offset:0x1e00
	v_mfma_f32_32x32x16_bf16 v[32:47], v[216:219], v[236:239], v[32:47]
	ds_read_b64_tr_b16 v[236:237], v152 offset:0x2600
	ds_read_b64_tr_b16 v[238:239], v152 offset:0x2e00
	v_mfma_f32_32x32x16_bf16 v[32:47], v[224:227], v[240:243], v[32:47]
	ds_read_b64_tr_b16 v[240:241], v152 offset:0x3600
	ds_read_b64_tr_b16 v[242:243], v152 offset:0x3e00
	s_waitcnt lgkmcnt(0)
	v_mfma_f32_32x32x16_bf16 v[16:31], v[132:135], v[228:231], v[16:31]
	v_max_f32_e32 v132, v81, v81
	v_max_f32_e32 v133, v80, v80
	v_max_f32_e32 v132, v133, v132
	v_max3_f32 v132, v132, v82, v83
	v_max3_f32 v132, v132, v84, v85
	v_max3_f32 v132, v132, v86, v87
	v_max3_f32 v132, v132, v88, v89
	v_max3_f32 v132, v132, v90, v91
	v_max3_f32 v132, v132, v92, v93
	v_mfma_f32_32x32x16_bf16 v[16:31], v[212:215], v[232:235], v[16:31]
	v_max3_f32 v132, v132, v94, v95
	v_max3_f32 v132, v132, v64, v65
	v_max3_f32 v132, v132, v66, v67
	v_max3_f32 v132, v132, v68, v69
	v_max3_f32 v132, v132, v70, v71
	v_max3_f32 v132, v132, v72, v73
	v_max3_f32 v132, v132, v74, v75
	v_max3_f32 v132, v132, v76, v77
	v_mfma_f32_32x32x16_bf16 v[16:31], v[216:219], v[236:239], v[16:31]
	v_max3_f32 v132, v132, v78, v79
	v_mov_b32_e32 v133, v132
	s_nop 1
	v_permlane32_swap_b32_e32 v132, v133
	v_max_f32_e32 v133, v133, v133
	v_max_f32_e32 v132, v132, v132
	v_max_f32_e32 v132, v132, v133
	v_sub_f32_e32 v133, v132, v188
	v_cmp_ge_f32_e32 vcc, s1, v133
	v_max_f32_e32 v133, v188, v188
	v_max_f32_e32 v132, v133, v132
	v_mfma_f32_32x32x16_bf16 v[16:31], v[224:227], v[240:243], v[16:31]
	v_sub_f32_e32 v133, v188, v132
	v_mul_f32_e32 v133, 0x3dd53b94, v133
	v_exp_f32_e32 v133, v133
	s_cmp_eq_u64 vcc, exec
	s_cselect_b64 s[6:7], -1, 0
	s_barrier
	s_waitcnt vmcnt(0)
	v_cndmask_b32_e64 v211, v133, 1.0, s[6:7]
	v_cmp_gt_f32_e32 vcc, 1.0, v211
	s_waitcnt vmcnt(4)
	ds_write_b128 v163, v[112:115]
	s_waitcnt vmcnt(3)
	ds_write_b128 v164, v[116:119]
	s_waitcnt vmcnt(2)
	ds_write_b128 v159, v[120:123] offset:32768
	s_waitcnt vmcnt(1)
	ds_write_b128 v159, v[124:127] offset:32896
	s_waitcnt vmcnt(0)
	ds_write_b128 v159, v[128:131] offset:33024
	s_cbranch_vccz .LBB0_2195
	s_and_saveexec_b64 s[10:11], s[4:5]
	ds_write_b32 v174, v211 offset:128
	s_or_b64 exec, exec, s[10:11]
	s_waitcnt lgkmcnt(0)
	v_add_u32_e32 v124, v137, v160
	ds_read_b128 v[112:115], v124 offset:224
	ds_read_b128 v[116:119], v124 offset:192
	ds_read_b128 v[120:123], v124 offset:160
	ds_read_b128 v[124:127], v124 offset:128
	s_waitcnt lgkmcnt(3)
	v_pk_mul_f32 v[12:13], v[12:13], v[112:113]
	s_waitcnt lgkmcnt(2)
	v_pk_mul_f32 v[8:9], v[8:9], v[116:117]
	s_waitcnt lgkmcnt(1)
	v_pk_mul_f32 v[4:5], v[4:5], v[120:121]
	v_pk_mul_f32 v[14:15], v[14:15], v[114:115]
	v_pk_mul_f32 v[10:11], v[10:11], v[118:119]
	v_pk_mul_f32 v[6:7], v[6:7], v[122:123]
	s_waitcnt lgkmcnt(0)
	v_pk_mul_f32 v[2:3], v[2:3], v[126:127]
	v_pk_mul_f32 v[0:1], v[0:1], v[124:125]
	v_pk_mul_f32 v[60:61], v[60:61], v[112:113]
	v_pk_mul_f32 v[56:57], v[56:57], v[116:117]
	v_pk_mul_f32 v[52:53], v[52:53], v[120:121]
	v_pk_mul_f32 v[62:63], v[62:63], v[114:115]
	v_pk_mul_f32 v[58:59], v[58:59], v[118:119]
	v_pk_mul_f32 v[54:55], v[54:55], v[122:123]
	v_pk_mul_f32 v[50:51], v[50:51], v[126:127]
	v_pk_mul_f32 v[48:49], v[48:49], v[124:125]
	v_pk_mul_f32 v[44:45], v[44:45], v[112:113]
	v_pk_mul_f32 v[40:41], v[40:41], v[116:117]
	v_pk_mul_f32 v[36:37], v[36:37], v[120:121]
	v_pk_mul_f32 v[46:47], v[46:47], v[114:115]
	v_pk_mul_f32 v[42:43], v[42:43], v[118:119]
	v_pk_mul_f32 v[38:39], v[38:39], v[122:123]
	v_pk_mul_f32 v[34:35], v[34:35], v[126:127]
	v_pk_mul_f32 v[32:33], v[32:33], v[124:125]
	v_pk_mul_f32 v[28:29], v[28:29], v[112:113]
	v_pk_mul_f32 v[24:25], v[24:25], v[116:117]
	v_pk_mul_f32 v[20:21], v[20:21], v[120:121]
	v_pk_mul_f32 v[30:31], v[30:31], v[114:115]
	v_pk_mul_f32 v[26:27], v[26:27], v[118:119]
	v_pk_mul_f32 v[22:23], v[22:23], v[122:123]
	v_pk_mul_f32 v[18:19], v[18:19], v[126:127]
	v_pk_mul_f32 v[16:17], v[16:17], v[124:125]

.LBB0_2201:
	s_setprio 0
	v_mov_b32_e32 v220, 0
	v_mov_b32_e32 v221, 0
	v_mov_b32_e32 v222, 0
	v_mov_b32_e32 v223, 0
	ds_read_b128 v[64:67], v156 offset:57344
	ds_read_b128 v[68:71], v191 offset:12288
	v_exp_f32_e32 v116, v116
	v_exp_f32_e32 v117, v117
	v_exp_f32_e32 v114, v114
	s_waitcnt lgkmcnt(1)
	v_mfma_f32_32x32x16_bf16 v[80:95], v[64:67], v[108:111], 0
	v_exp_f32_e32 v115, v115
	v_exp_f32_e32 v118, v118
	v_exp_f32_e32 v119, v119
	v_exp_f32_e32 v113, v113
	s_waitcnt lgkmcnt(0)
	v_mfma_f32_32x32x16_bf16 v[64:79], v[68:71], v[108:111], 0
	ds_read_b128 v[108:111], v169 offset:57344
	ds_read_b128 v[142:145], v193 offset:12288
	s_waitcnt lgkmcnt(1)
	v_mfma_f32_32x32x16_bf16 v[80:95], v[108:111], v[104:107], v[80:95]
	s_waitcnt lgkmcnt(0)
	v_mfma_f32_32x32x16_bf16 v[64:79], v[142:145], v[104:107], v[64:79]
	ds_read_b128 v[104:107], v168 offset:57344
	ds_read_b128 v[108:111], v192 offset:12288
	s_waitcnt lgkmcnt(1)
	v_mfma_f32_32x32x16_bf16 v[80:95], v[104:107], v[100:103], v[80:95]
	s_waitcnt lgkmcnt(0)
	v_mfma_f32_32x32x16_bf16 v[64:79], v[108:111], v[100:103], v[64:79]
	ds_read_b128 v[100:103], v167 offset:57344
	ds_read_b128 v[104:107], v200 offset:12288
	v_exp_f32_e32 v108, v124
	v_exp_f32_e32 v109, v125
	v_exp_f32_e32 v110, v120
	v_exp_f32_e32 v111, v121
	v_exp_f32_e32 v120, v122
	v_exp_f32_e32 v121, v123
	s_waitcnt lgkmcnt(1)
	v_mfma_f32_32x32x16_bf16 v[80:95], v[100:103], v[96:99], v[80:95]
	v_exp_f32_e32 v122, v112
	s_waitcnt lgkmcnt(0)
	v_mfma_f32_32x32x16_bf16 v[64:79], v[104:107], v[96:99], v[64:79]
	ds_read_b128 v[96:99], v165 offset:57344
	ds_read_b128 v[100:103], v201 offset:12288
	ds_read_b128 v[104:107], v139
	s_waitcnt lgkmcnt(0)
	v_mfma_f32_32x32x16_bf16 v[80:95], v[96:99], v[104:107], v[80:95]
	v_mfma_f32_32x32x16_bf16 v[64:79], v[100:103], v[104:107], v[64:79]
	ds_read_b128 v[96:99], v166 offset:57344
	ds_read_b128 v[100:103], v204 offset:12288
	ds_read_b128 v[104:107], v139 offset:1024
	s_waitcnt lgkmcnt(0)
	v_mfma_f32_32x32x16_bf16 v[80:95], v[96:99], v[104:107], v[80:95]
	v_mfma_f32_32x32x16_bf16 v[64:79], v[100:103], v[104:107], v[64:79]
	ds_read_b128 v[96:99], v158 offset:57344
	ds_read_b128 v[100:103], v202 offset:12288
	ds_read_b128 v[104:107], v139 offset:2048
	s_waitcnt lgkmcnt(0)
	v_mfma_f32_32x32x16_bf16 v[80:95], v[96:99], v[104:107], v[80:95]
	v_mfma_f32_32x32x16_bf16 v[64:79], v[100:103], v[104:107], v[64:79]
	ds_read_b128 v[96:99], v157 offset:57344
	ds_read_b128 v[100:103], v203 offset:12288
	ds_read_b128 v[104:107], v139 offset:3072
	s_waitcnt lgkmcnt(0)
	v_mfma_f32_32x32x16_bf16 v[80:95], v[96:99], v[104:107], v[80:95]
	v_mfma_f32_32x32x16_bf16 v[64:79], v[100:103], v[104:107], v[64:79]
	ds_read_b128 v[96:99], v154 offset:57344
	ds_read_b128 v[100:103], v206 offset:12288
	ds_read_b128 v[104:107], v139 offset:4096
	s_waitcnt lgkmcnt(0)
	v_mfma_f32_32x32x16_bf16 v[80:95], v[96:99], v[104:107], v[80:95]
	v_mfma_f32_32x32x16_bf16 v[64:79], v[100:103], v[104:107], v[64:79]
	ds_read_b128 v[96:99], v153 offset:57344
	ds_read_b128 v[100:103], v205 offset:12288
	ds_read_b128 v[104:107], v139 offset:5120
	s_waitcnt lgkmcnt(0)
	v_mfma_f32_32x32x16_bf16 v[80:95], v[96:99], v[104:107], v[80:95]
	v_mfma_f32_32x32x16_bf16 v[64:79], v[100:103], v[104:107], v[64:79]
	ds_read_b128 v[96:99], v180 offset:57344
	ds_read_b128 v[100:103], v207 offset:12288
	ds_read_b128 v[104:107], v139 offset:6144
	s_waitcnt lgkmcnt(0)
	v_mfma_f32_32x32x16_bf16 v[80:95], v[96:99], v[104:107], v[80:95]
	v_mfma_f32_32x32x16_bf16 v[64:79], v[100:103], v[104:107], v[64:79]
	ds_read_b128 v[96:99], v179 offset:57344
	ds_read_b128 v[100:103], v208 offset:12288
	ds_read_b128 v[104:107], v139 offset:7168
	s_waitcnt lgkmcnt(0)
	v_mfma_f32_32x32x16_bf16 v[80:95], v[96:99], v[104:107], v[80:95]
	v_add_f32_e32 v96, 0, v133
	v_add_f32_e32 v96, v214, v96
	v_add_f32_e32 v96, v134, v96
	v_add_f32_e32 v96, v215, v96
	v_add_f32_e32 v96, v213, v96
	v_add_f32_e32 v96, v216, v96
	v_add_f32_e32 v96, v135, v96
	v_add_f32_e32 v96, v212, v96
	v_add_f32_e32 v96, v146, v96
	v_add_f32_e32 v96, v148, v96
	v_add_f32_e32 v96, v147, v96
	v_add_f32_e32 v96, v149, v96
	v_mfma_f32_32x32x16_bf16 v[64:79], v[100:103], v[104:107], v[64:79]
	v_exp_f32_e32 v106, v126
	v_add_f32_e32 v96, v128, v96
	v_exp_f32_e32 v107, v127
	v_add_f32_e32 v96, v130, v96
	v_add_f32_e32 v96, v129, v96
	v_add_f32_e32 v96, v131, v96
	v_add_f32_e32 v96, v106, v96
	v_add_f32_e32 v96, v107, v96
	v_add_f32_e32 v96, v108, v96
	v_add_f32_e32 v96, v109, v96
	v_add_f32_e32 v96, v110, v96
	v_add_f32_e32 v96, v111, v96
	v_add_f32_e32 v96, v116, v96
	v_add_f32_e32 v96, v117, v96
	v_add_f32_e32 v96, v114, v96
	v_add_f32_e32 v96, v115, v96
	v_add_f32_e32 v96, v120, v96
	v_add_f32_e32 v96, v121, v96
	v_add_f32_e32 v96, v118, v96
	v_add_f32_e32 v96, v119, v96
	v_add_f32_e32 v96, v122, v96
	v_add_f32_e32 v96, v113, v96
	v_mov_b32_e32 v97, v96
	v_cvt_pk_bf16_f32 v98, v133, v214
	v_cvt_pk_bf16_f32 v99, v134, v215
	v_cvt_pk_bf16_f32 v100, v213, v216
	v_cvt_pk_bf16_f32 v101, v135, v212
	s_nop 1
	v_permlane32_swap_b32_e32 v96, v97
	v_permlane32_swap_b32_e32 v98, v100
	v_permlane32_swap_b32_e32 v99, v101
	v_cvt_pk_bf16_f32 v102, v146, v148
	v_cvt_pk_bf16_f32 v103, v147, v149
	v_cvt_pk_bf16_f32 v104, v128, v130
	v_cvt_pk_bf16_f32 v105, v129, v131
	v_cvt_pk_bf16_f32 v106, v106, v107
	v_cvt_pk_bf16_f32 v107, v108, v109
	v_cvt_pk_bf16_f32 v108, v110, v111
	v_cvt_pk_bf16_f32 v109, v116, v117
	v_cvt_pk_bf16_f32 v110, v114, v115
	v_cvt_pk_bf16_f32 v111, v120, v121
	v_cvt_pk_bf16_f32 v112, v118, v119
	v_cvt_pk_bf16_f32 v113, v122, v113
	s_nop 0
	v_permlane32_swap_b32_e32 v102, v104
	v_permlane32_swap_b32_e32 v103, v105
	v_permlane32_swap_b32_e32 v106, v108
	v_permlane32_swap_b32_e32 v107, v109
	v_permlane32_swap_b32_e32 v110, v112
	v_permlane32_swap_b32_e32 v111, v113
	ds_read_b64_tr_b16 v[114:115], v152 offset:0
	ds_read_b64_tr_b16 v[116:117], v152 offset:0x800
	ds_read_b64_tr_b16 v[118:119], v152 offset:0x1000
	ds_read_b64_tr_b16 v[120:121], v152 offset:0x1800
	ds_read_b64_tr_b16 v[122:123], v152 offset:0x2000
	ds_read_b64_tr_b16 v[124:125], v152 offset:0x2800
	ds_read_b64_tr_b16 v[126:127], v152 offset:0x3000
	ds_read_b64_tr_b16 v[128:129], v152 offset:0x3800
	s_waitcnt lgkmcnt(0)
	s_nop 0
	v_mfma_f32_32x32x16_bf16 v[0:15], v[98:101], v[114:117], v[0:15]
	ds_read_b64_tr_b16 v[114:115], v152 offset:0x200
	ds_read_b64_tr_b16 v[116:117], v152 offset:0xa00
	v_mfma_f32_32x32x16_bf16 v[0:15], v[102:105], v[118:121], v[0:15]
	ds_read_b64_tr_b16 v[118:119], v152 offset:0x1200
	ds_read_b64_tr_b16 v[120:121], v152 offset:0x1a00
	v_mfma_f32_32x32x16_bf16 v[0:15], v[106:109], v[122:125], v[0:15]
	ds_read_b64_tr_b16 v[122:123], v152 offset:0x2200
	ds_read_b64_tr_b16 v[124:125], v152 offset:0x2a00
	v_mfma_f32_32x32x16_bf16 v[0:15], v[110:113], v[126:129], v[0:15]
	ds_read_b64_tr_b16 v[126:127], v152 offset:0x3200
	ds_read_b64_tr_b16 v[128:129], v152 offset:0x3a00
	s_waitcnt lgkmcnt(0)
	v_mfma_f32_32x32x16_bf16 v[48:63], v[98:101], v[114:117], v[48:63]
	ds_read_b64_tr_b16 v[114:115], v152 offset:0x400
	ds_read_b64_tr_b16 v[116:117], v152 offset:0xc00
	v_mfma_f32_32x32x16_bf16 v[48:63], v[102:105], v[118:121], v[48:63]
	ds_read_b64_tr_b16 v[118:119], v152 offset:0x1400
	ds_read_b64_tr_b16 v[120:121], v152 offset:0x1c00
	v_mfma_f32_32x32x16_bf16 v[48:63], v[106:109], v[122:125], v[48:63]
	ds_read_b64_tr_b16 v[122:123], v152 offset:0x2400
	ds_read_b64_tr_b16 v[124:125], v152 offset:0x2c00
	v_mfma_f32_32x32x16_bf16 v[48:63], v[110:113], v[126:129], v[48:63]
	ds_read_b64_tr_b16 v[126:127], v152 offset:0x3400
	ds_read_b64_tr_b16 v[128:129], v152 offset:0x3c00
	s_waitcnt lgkmcnt(0)
	v_mfma_f32_32x32x16_bf16 v[32:47], v[98:101], v[114:117], v[32:47]
	ds_read_b64_tr_b16 v[114:115], v152 offset:0x600
	ds_read_b64_tr_b16 v[116:117], v152 offset:0xe00
	v_mfma_f32_32x32x16_bf16 v[32:47], v[102:105], v[118:121], v[32:47]
	ds_read_b64_tr_b16 v[118:119], v152 offset:0x1600
	ds_read_b64_tr_b16 v[120:121], v152 offset:0x1e00
	v_mfma_f32_32x32x16_bf16 v[32:47], v[106:109], v[122:125], v[32:47]
	ds_read_b64_tr_b16 v[122:123], v152 offset:0x2600
	ds_read_b64_tr_b16 v[124:125], v152 offset:0x2e00
	v_mfma_f32_32x32x16_bf16 v[32:47], v[110:113], v[126:129], v[32:47]
	ds_read_b64_tr_b16 v[126:127], v152 offset:0x3600
	ds_read_b64_tr_b16 v[128:129], v152 offset:0x3e00
	s_waitcnt lgkmcnt(0)
	v_mfma_f32_32x32x16_bf16 v[16:31], v[98:101], v[114:117], v[16:31]
	v_max_f32_e32 v98, v81, v81
	v_max_f32_e32 v99, v80, v80
	v_max_f32_e32 v98, v99, v98
	v_max3_f32 v98, v98, v82, v83
	v_max3_f32 v98, v98, v84, v85
	v_max3_f32 v98, v98, v86, v87
	v_max3_f32 v98, v98, v88, v89
	v_max3_f32 v98, v98, v90, v91
	v_max3_f32 v98, v98, v92, v93
	v_mfma_f32_32x32x16_bf16 v[16:31], v[102:105], v[118:121], v[16:31]
	v_max3_f32 v98, v98, v94, v95
	v_max3_f32 v98, v98, v64, v65
	v_max3_f32 v98, v98, v66, v67
	v_max3_f32 v98, v98, v68, v69
	v_max3_f32 v98, v98, v70, v71
	v_max3_f32 v98, v98, v72, v73
	v_max3_f32 v98, v98, v74, v75
	v_max3_f32 v98, v98, v76, v77
	v_mfma_f32_32x32x16_bf16 v[16:31], v[106:109], v[122:125], v[16:31]
	v_max3_f32 v98, v98, v78, v79
	v_mov_b32_e32 v99, v98
	s_nop 1
	v_permlane32_swap_b32_e32 v98, v99
	v_max_f32_e32 v99, v99, v99
	v_max_f32_e32 v98, v98, v98
	v_max_f32_e32 v98, v98, v99
	v_sub_f32_e32 v99, v98, v188
	v_cmp_ge_f32_e32 vcc, s1, v99
	v_max_f32_e32 v99, v188, v188
	v_max_f32_e32 v99, v99, v98
	v_mfma_f32_32x32x16_bf16 v[16:31], v[110:113], v[126:129], v[16:31]
	v_sub_f32_e32 v98, v188, v99
	v_mul_f32_e32 v98, 0x3dd53b94, v98
	v_exp_f32_e32 v98, v98
	s_cmp_eq_u64 vcc, exec
	s_cselect_b64 s[6:7], -1, 0
	v_cndmask_b32_e64 v98, v98, 1.0, s[6:7]
	v_cmp_gt_f32_e32 vcc, 1.0, v98
	s_barrier
	s_cbranch_vccz .LBB0_2205
	s_and_saveexec_b64 s[10:11], s[4:5]
	ds_write_b32 v174, v98 offset:128
	s_or_b64 exec, exec, s[10:11]
	s_waitcnt lgkmcnt(0)
	v_add_u32_e32 v112, v137, v160
	ds_read_b128 v[100:103], v112 offset:224
	ds_read_b128 v[104:107], v112 offset:192
	ds_read_b128 v[108:111], v112 offset:160
	ds_read_b128 v[112:115], v112 offset:128
	s_waitcnt lgkmcnt(3)
	v_pk_mul_f32 v[12:13], v[12:13], v[100:101]
	s_waitcnt lgkmcnt(2)
	v_pk_mul_f32 v[8:9], v[8:9], v[104:105]
	s_waitcnt lgkmcnt(1)
	v_pk_mul_f32 v[4:5], v[4:5], v[108:109]
	v_pk_mul_f32 v[14:15], v[14:15], v[102:103]
	v_pk_mul_f32 v[10:11], v[10:11], v[106:107]
	v_pk_mul_f32 v[6:7], v[6:7], v[110:111]
	s_waitcnt lgkmcnt(0)
	v_pk_mul_f32 v[2:3], v[2:3], v[114:115]
	v_pk_mul_f32 v[0:1], v[0:1], v[112:113]
	v_pk_mul_f32 v[60:61], v[60:61], v[100:101]
	v_pk_mul_f32 v[56:57], v[56:57], v[104:105]
	v_pk_mul_f32 v[52:53], v[52:53], v[108:109]
	v_pk_mul_f32 v[62:63], v[62:63], v[102:103]
	v_pk_mul_f32 v[58:59], v[58:59], v[106:107]
	v_pk_mul_f32 v[54:55], v[54:55], v[110:111]
	v_pk_mul_f32 v[50:51], v[50:51], v[114:115]
	v_pk_mul_f32 v[48:49], v[48:49], v[112:113]
	v_pk_mul_f32 v[44:45], v[44:45], v[100:101]
	v_pk_mul_f32 v[40:41], v[40:41], v[104:105]
	v_pk_mul_f32 v[36:37], v[36:37], v[108:109]
	v_pk_mul_f32 v[46:47], v[46:47], v[102:103]
	v_pk_mul_f32 v[42:43], v[42:43], v[106:107]
	v_pk_mul_f32 v[38:39], v[38:39], v[110:111]
	v_pk_mul_f32 v[34:35], v[34:35], v[114:115]
	v_pk_mul_f32 v[32:33], v[32:33], v[112:113]
	v_pk_mul_f32 v[28:29], v[28:29], v[100:101]
	v_pk_mul_f32 v[24:25], v[24:25], v[104:105]
	v_pk_mul_f32 v[20:21], v[20:21], v[108:109]
	v_pk_mul_f32 v[30:31], v[30:31], v[102:103]
	v_pk_mul_f32 v[26:27], v[26:27], v[106:107]
	v_pk_mul_f32 v[22:23], v[22:23], v[110:111]
	v_pk_mul_f32 v[18:19], v[18:19], v[114:115]
	v_pk_mul_f32 v[16:17], v[16:17], v[112:113]
